# P3 chunk scan rewritten by hand: role-specialized V/O wave code paths, 4-deep operand prefetch issued in the LDS-write wait window, dword-packed o stores via DPP, no dummy MFMAs/stores; on top of hand
# speedup vs baseline: 1.0075x; 1.0075x over previous
; #define LAS __attribute__((address_space(3)))
; template <int PROBE>
; __device__ __forceinline__ void p3_scan_fast(Frame& F, const Args& a) {
;     ...
;     const int w = F.wave, lane = F.lane, fr = lane & 15, fq = lane >> 4, mt = w & 3; const bool vw = w < 4;
;     for (int unit = F.vcu; unit < NB * NH * 4; unit += F.G) {
;         const int bh = unit >> 2, s = unit & 3, h = bh % NH, b = bh / NH;
;         f32x4 accS[2] = {(f32x4){0.f, 0.f, 0.f, 0.f}, (f32x4){0.f, 0.f, 0.f, 0.f}};
;         for (int i = F.tid; i < 32 * ST_LD / 4; i += 512) ((LAS unsigned*)ST)[i] = 0u;
;         __syncthreads();
;         LAS unsigned char* VTw = vw ? VT : VT + 32 * VT_LD;
;         bf16_t* Odummy = (bf16_t*)(a.ws + WS_POOLED) - (size_t)65536 + (size_t)F.vcu * 64;
;         const bf16_t* Asrc = (vw ? NW : QD) + mt * 2048 + lane * 8;
;         const bf16_t* Ksrc = KDT + w * 1024 + lane * 8;
;         const bf16_t* Xsrc = vw ? UT + (s * 4 + mt) * 512 + lane * 8 : QK + mt * 1024 + lane * 8;
;         const size_t xstride = vw ? 8192 : 4096; const int xstep = vw ? 0 : 512;
;     ...
;         ScanOps opA, opB, opC;
;         SCAN_LOAD(opA, 0); SCAN_LOAD(opB, 1); if (PROBE >= 3) SCAN_LOAD(opC, 2);
.LBB0_776:
	s_cmp_gt_i32 s4, 3
	s_cselect_b64 s[0:1], -1, 0
	s_cmp_lt_i32 s5, 4
	s_cselect_b64 s[2:3], -1, 0
	s_or_b64 s[0:1], s[0:1], s[2:3]
	s_and_b64 vcc, exec, s[0:1]
	s_cbranch_vccnz .LBB0_850
	v_readlane_b32 s0, v255, 3
	s_cmpk_gt_i32 s0, 0xff
	v_readlane_b32 s1, v255, 4
	s_cbranch_scc1 .LBB0_800
	v_readlane_b32 s0, v255, 3
	s_lshr_b32 s7, s82, 6
	s_and_b32 s8, s7, 3
	s_lshr_b32 s6, s7, 2
	s_lshr_b32 s2, s0, 2
	s_and_b32 s3, s0, 3
	s_and_b32 s4, s2, 15
	s_lshr_b32 s5, s2, 4
	s_mul_i32 s9, s2, 33
	v_lshlrev_b32_e32 v1, 4, v254
	v_and_b32_e32 v12, 15, v254
	v_lshrrev_b32_e32 v13, 4, v254
	v_mov_b32_e32 v5, 0
	s_lshl_b32 s10, s8, 12
	v_add_u32_e32 v2, s10, v1
	s_lshl_b32 s10, s7, 11
	v_add_u32_e32 v3, s10, v1
	s_lshl_b32 s10, s3, 2
	s_add_i32 s10, s10, s8
	s_lshl_b32 s10, s10, 10
	s_lshl_b32 s11, s8, 11
	s_cmp_eq_u32 s6, 0
	s_cselect_b32 s10, s10, s11
	v_add_u32_e32 v4, s10, v1
	s_mov_b32 s10, 0x100000
	s_mov_b32 s11, 0x4300000
	s_cselect_b32 s10, s10, s11
	s_lshl_b32 s11, s9, 14
	s_add_u32 s16, s26, s10
	s_addc_u32 s17, s27, 0
	s_add_u32 s16, s16, s11
	s_addc_u32 s17, s17, 0
	s_add_u32 s18, s26, 0x6400000
	s_addc_u32 s19, s27, 0
	s_add_u32 s18, s18, s11
	s_addc_u32 s19, s19, 0
	s_lshl_b32 s34, s9, 13
	s_cmp_eq_u32 s6, 0
	s_mov_b32 s10, 0x2200000
	s_mov_b32 s20, 0x8500000
	s_cselect_b32 s10, s10, s20
	s_cselect_b32 s11, s11, s34
	s_movk_i32 s35, 0x4000
	s_movk_i32 s20, 0x2000
	s_cselect_b32 s35, s35, s20
	s_add_u32 s20, s26, s10
	s_addc_u32 s21, s27, 0
	s_add_u32 s20, s20, s11
	s_addc_u32 s21, s21, 0
	s_lshl_b32 s10, s9, 2
	s_add_u32 s28, s26, 0x9580000
	s_addc_u32 s29, s27, 0
	s_add_u32 s28, s28, s10
	s_addc_u32 s29, s29, 0
	s_lshl_b32 s10, s5, 23
	s_add_u32 s42, s26, 0xcc00000
	s_addc_u32 s43, s27, 0
	s_add_u32 s42, s42, s10
	s_addc_u32 s43, s43, 0
	s_add_u32 s30, s26, 0x19180000
	s_addc_u32 s31, s27, 0
	v_and_b32_e32 v6, 1, v12
	v_cmp_eq_u32_e64 s[40:41], 0, v6
	v_lshl_add_u32 v7, v6, 4, v12
	v_sub_u32_e32 v7, v7, v6
	s_lshl_b32 s10, s4, 7
	s_lshl_b32 s11, s3, 5
	s_add_i32 s10, s10, s11
	v_add_lshl_u32 v7, v7, s10, 1
	s_lshl_b32 s10, s8, 4
	v_lshl_add_u32 v6, v13, 2, s10
	v_lshl_add_u32 v6, v6, 12, v7
	v_add_u32_e32 v7, 0x3000, v6
	v_add_u32_e32 v6, 0x1000, v6
	s_movk_i32 s10, 0x110
	v_mul_u32_u24_e32 v8, s10, v12
	v_lshl_add_u32 v11, v13, 3, v8
	s_lshl_b32 s10, s7, 5
	v_add_u32_e32 v11, s10, v11
	v_lshl_add_u32 v8, v13, 4, v8
	s_movk_i32 s10, 0x90
	v_mul_u32_u24_e32 v10, s10, v12
	v_lshl_add_u32 v9, v13, 3, v10
	s_lshl_b32 s10, s8, 5
	s_addk_i32 s10, 0x2200
	v_add_u32_e32 v9, s10, v9
	v_lshl_add_u32 v10, v13, 4, v10
	v_add_u32_e32 v10, 0x2200, v10
	v_lshlrev_b32_e32 v15, 4, v0
	v_mov_b32_e32 v224, 0
	v_mov_b32_e32 v225, 0
	v_mov_b32_e32 v226, 0
	v_mov_b32_e32 v227, 0
	ds_write_b128 v15, v[224:227]
	ds_write_b128 v15, v[224:227] offset:8192
	v_mov_b32_e32 v216, 0
	v_mov_b32_e32 v217, 0
	v_mov_b32_e32 v218, 0
	v_mov_b32_e32 v219, 0
	v_mov_b32_e32 v220, 0
	v_mov_b32_e32 v221, 0
	v_mov_b32_e32 v222, 0
	v_mov_b32_e32 v223, 0
	s_waitcnt lgkmcnt(0)
	s_barrier
	s_cmp_eq_u32 s6, 0
	s_cbranch_scc0 .Lp3_owave
	global_load_dwordx4 v[16:19], v2, s[16:17] offset:0
	global_load_dwordx4 v[20:23], v2, s[16:17] offset:1024
	global_load_dwordx4 v[24:27], v2, s[16:17] offset:2048
	global_load_dwordx4 v[28:31], v2, s[16:17] offset:3072
	global_load_dwordx4 v[32:35], v3, s[18:19] offset:0
	global_load_dwordx4 v[36:39], v3, s[18:19] offset:1024
	global_load_dwordx4 v[40:43], v4, s[20:21]
	global_load_dword v48, v5, s[28:29]
	s_add_u32 s16, s16, 0x4000
	s_addc_u32 s17, s17, 0
	s_add_u32 s18, s18, 0x4000
	s_addc_u32 s19, s19, 0
	s_add_u32 s20, s20, s35
	s_addc_u32 s21, s21, 0
	s_add_u32 s28, s28, 4
	s_addc_u32 s29, s29, 0
	global_load_dwordx4 v[50:53], v2, s[16:17] offset:0
	global_load_dwordx4 v[54:57], v2, s[16:17] offset:1024
	global_load_dwordx4 v[58:61], v2, s[16:17] offset:2048
	global_load_dwordx4 v[62:65], v2, s[16:17] offset:3072
	global_load_dwordx4 v[66:69], v3, s[18:19] offset:0
	global_load_dwordx4 v[70:73], v3, s[18:19] offset:1024
	global_load_dwordx4 v[74:77], v4, s[20:21]
	global_load_dword v82, v5, s[28:29]
	s_add_u32 s16, s16, 0x4000
	s_addc_u32 s17, s17, 0
	s_add_u32 s18, s18, 0x4000
	s_addc_u32 s19, s19, 0
	s_add_u32 s20, s20, s35
	s_addc_u32 s21, s21, 0
	s_add_u32 s28, s28, 4
	s_addc_u32 s29, s29, 0
	global_load_dwordx4 v[84:87], v2, s[16:17] offset:0
	global_load_dwordx4 v[88:91], v2, s[16:17] offset:1024
	global_load_dwordx4 v[92:95], v2, s[16:17] offset:2048
	global_load_dwordx4 v[96:99], v2, s[16:17] offset:3072
	global_load_dwordx4 v[100:103], v3, s[18:19] offset:0
	global_load_dwordx4 v[104:107], v3, s[18:19] offset:1024
	global_load_dwordx4 v[108:111], v4, s[20:21]
	global_load_dword v116, v5, s[28:29]
	s_add_u32 s16, s16, 0x4000
	s_addc_u32 s17, s17, 0
	s_add_u32 s18, s18, 0x4000
	s_addc_u32 s19, s19, 0
	s_add_u32 s20, s20, s35
	s_addc_u32 s21, s21, 0
	s_add_u32 s28, s28, 4
	s_addc_u32 s29, s29, 0
	s_mov_b32 s9, 0
.Lp3_vloop:
	ds_read_b128 v[160:163], v8 offset:0
	ds_read_b128 v[176:179], v8 offset:4352
	ds_read_b128 v[164:167], v8 offset:64
	ds_read_b128 v[180:183], v8 offset:4416
	ds_read_b128 v[168:171], v8 offset:128
	ds_read_b128 v[184:187], v8 offset:4480
	ds_read_b128 v[172:175], v8 offset:192
	ds_read_b128 v[188:191], v8 offset:4544
	s_waitcnt vmcnt(16)
	v_lshlrev_b32_e32 v208, 16, v40
	v_and_b32_e32 v209, 0xffff0000, v40
	v_lshlrev_b32_e32 v210, 16, v41
	v_and_b32_e32 v211, 0xffff0000, v41
	v_lshlrev_b32_e32 v212, 16, v42
	v_and_b32_e32 v213, 0xffff0000, v42
	v_lshlrev_b32_e32 v214, 16, v43
	v_and_b32_e32 v215, 0xffff0000, v43
	s_waitcnt lgkmcnt(7)
	v_mfma_f32_16x16x32_bf16 v[208:211], v[16:19], v[160:163], v[208:211]
	s_waitcnt lgkmcnt(6)
	v_mfma_f32_16x16x32_bf16 v[212:215], v[16:19], v[176:179], v[212:215]
	s_waitcnt lgkmcnt(5)
	v_mfma_f32_16x16x32_bf16 v[208:211], v[20:23], v[164:167], v[208:211]
	s_waitcnt lgkmcnt(4)
	v_mfma_f32_16x16x32_bf16 v[212:215], v[20:23], v[180:183], v[212:215]
	s_waitcnt lgkmcnt(3)
	v_mfma_f32_16x16x32_bf16 v[208:211], v[24:27], v[168:171], v[208:211]
	s_waitcnt lgkmcnt(2)
	v_mfma_f32_16x16x32_bf16 v[212:215], v[24:27], v[184:187], v[212:215]
	s_waitcnt lgkmcnt(1)
	v_mfma_f32_16x16x32_bf16 v[208:211], v[28:31], v[172:175], v[208:211]
	s_waitcnt lgkmcnt(0)
	v_mfma_f32_16x16x32_bf16 v[212:215], v[28:31], v[188:191], v[212:215]
	s_nop 7
	v_cvt_pk_bf16_f32 v224, v208, v209
	v_cvt_pk_bf16_f32 v225, v210, v211
	v_cvt_pk_bf16_f32 v226, v212, v213
	v_cvt_pk_bf16_f32 v227, v214, v215
	ds_write_b64 v9, v[224:225]
	ds_write_b64 v9, v[226:227] offset:2304
	s_waitcnt lgkmcnt(0)
	s_barrier
	ds_read_b128 v[192:195], v10 offset:0
	ds_read_b128 v[200:203], v10 offset:2304
	ds_read_b128 v[196:199], v10 offset:64
	ds_read_b128 v[204:207], v10 offset:2368
	v_pk_mul_f32 v[216:217], v[216:217], v[48:49] op_sel_hi:[1,0]
	v_pk_mul_f32 v[218:219], v[218:219], v[48:49] op_sel_hi:[1,0]
	v_pk_mul_f32 v[220:221], v[220:221], v[48:49] op_sel_hi:[1,0]
	v_pk_mul_f32 v[222:223], v[222:223], v[48:49] op_sel_hi:[1,0]
	s_waitcnt lgkmcnt(3)
	v_mfma_f32_16x16x32_bf16 v[216:219], v[32:35], v[192:195], v[216:219]
	s_waitcnt lgkmcnt(2)
	v_mfma_f32_16x16x32_bf16 v[220:223], v[32:35], v[200:203], v[220:223]
	s_waitcnt lgkmcnt(1)
	v_mfma_f32_16x16x32_bf16 v[216:219], v[36:39], v[196:199], v[216:219]
	s_waitcnt lgkmcnt(0)
	v_mfma_f32_16x16x32_bf16 v[220:223], v[36:39], v[204:207], v[220:223]
	s_nop 7
	v_cvt_pk_bf16_f32 v228, v216, v217
	v_cvt_pk_bf16_f32 v229, v218, v219
	v_cvt_pk_bf16_f32 v230, v220, v221
	v_cvt_pk_bf16_f32 v231, v222, v223
	ds_write_b64 v11, v[228:229]
	ds_write_b64 v11, v[230:231] offset:4352
	global_load_dwordx4 v[118:121], v2, s[16:17] offset:0
	global_load_dwordx4 v[122:125], v2, s[16:17] offset:1024
	global_load_dwordx4 v[126:129], v2, s[16:17] offset:2048
	global_load_dwordx4 v[130:133], v2, s[16:17] offset:3072
	global_load_dwordx4 v[134:137], v3, s[18:19] offset:0
	global_load_dwordx4 v[138:141], v3, s[18:19] offset:1024
	global_load_dwordx4 v[142:145], v4, s[20:21]
	global_load_dword v150, v5, s[28:29]
	s_add_u32 s16, s16, 0x4000
	s_addc_u32 s17, s17, 0
	s_add_u32 s18, s18, 0x4000
	s_addc_u32 s19, s19, 0
	s_add_u32 s20, s20, s35
	s_addc_u32 s21, s21, 0
	s_add_u32 s28, s28, 4
	s_addc_u32 s29, s29, 0
	s_waitcnt lgkmcnt(0)
	s_barrier
	ds_read_b128 v[160:163], v8 offset:0
	ds_read_b128 v[176:179], v8 offset:4352
	ds_read_b128 v[164:167], v8 offset:64
	ds_read_b128 v[180:183], v8 offset:4416
	ds_read_b128 v[168:171], v8 offset:128
	ds_read_b128 v[184:187], v8 offset:4480
	ds_read_b128 v[172:175], v8 offset:192
	ds_read_b128 v[188:191], v8 offset:4544
	s_waitcnt vmcnt(16)
	v_lshlrev_b32_e32 v208, 16, v74
	v_and_b32_e32 v209, 0xffff0000, v74
	v_lshlrev_b32_e32 v210, 16, v75
	v_and_b32_e32 v211, 0xffff0000, v75
	v_lshlrev_b32_e32 v212, 16, v76
	v_and_b32_e32 v213, 0xffff0000, v76
	v_lshlrev_b32_e32 v214, 16, v77
	v_and_b32_e32 v215, 0xffff0000, v77
	s_waitcnt lgkmcnt(7)
	v_mfma_f32_16x16x32_bf16 v[208:211], v[50:53], v[160:163], v[208:211]
	s_waitcnt lgkmcnt(6)
	v_mfma_f32_16x16x32_bf16 v[212:215], v[50:53], v[176:179], v[212:215]
	s_waitcnt lgkmcnt(5)
	v_mfma_f32_16x16x32_bf16 v[208:211], v[54:57], v[164:167], v[208:211]
	s_waitcnt lgkmcnt(4)
	v_mfma_f32_16x16x32_bf16 v[212:215], v[54:57], v[180:183], v[212:215]
	s_waitcnt lgkmcnt(3)
	v_mfma_f32_16x16x32_bf16 v[208:211], v[58:61], v[168:171], v[208:211]
	s_waitcnt lgkmcnt(2)
	v_mfma_f32_16x16x32_bf16 v[212:215], v[58:61], v[184:187], v[212:215]
	s_waitcnt lgkmcnt(1)
	v_mfma_f32_16x16x32_bf16 v[208:211], v[62:65], v[172:175], v[208:211]
	s_waitcnt lgkmcnt(0)
	v_mfma_f32_16x16x32_bf16 v[212:215], v[62:65], v[188:191], v[212:215]
	s_nop 7
	v_cvt_pk_bf16_f32 v224, v208, v209
	v_cvt_pk_bf16_f32 v225, v210, v211
	v_cvt_pk_bf16_f32 v226, v212, v213
	v_cvt_pk_bf16_f32 v227, v214, v215
	ds_write_b64 v9, v[224:225]
	ds_write_b64 v9, v[226:227] offset:2304
	s_waitcnt lgkmcnt(0)
	s_barrier
	ds_read_b128 v[192:195], v10 offset:0
	ds_read_b128 v[200:203], v10 offset:2304
	ds_read_b128 v[196:199], v10 offset:64
	ds_read_b128 v[204:207], v10 offset:2368
	v_pk_mul_f32 v[216:217], v[216:217], v[82:83] op_sel_hi:[1,0]
	v_pk_mul_f32 v[218:219], v[218:219], v[82:83] op_sel_hi:[1,0]
	v_pk_mul_f32 v[220:221], v[220:221], v[82:83] op_sel_hi:[1,0]
	v_pk_mul_f32 v[222:223], v[222:223], v[82:83] op_sel_hi:[1,0]
	s_waitcnt lgkmcnt(3)
	v_mfma_f32_16x16x32_bf16 v[216:219], v[66:69], v[192:195], v[216:219]
	s_waitcnt lgkmcnt(2)
	v_mfma_f32_16x16x32_bf16 v[220:223], v[66:69], v[200:203], v[220:223]
	s_waitcnt lgkmcnt(1)
	v_mfma_f32_16x16x32_bf16 v[216:219], v[70:73], v[196:199], v[216:219]
	s_waitcnt lgkmcnt(0)
	v_mfma_f32_16x16x32_bf16 v[220:223], v[70:73], v[204:207], v[220:223]
	s_nop 7
	v_cvt_pk_bf16_f32 v228, v216, v217
	v_cvt_pk_bf16_f32 v229, v218, v219
	v_cvt_pk_bf16_f32 v230, v220, v221
	v_cvt_pk_bf16_f32 v231, v222, v223
	ds_write_b64 v11, v[228:229]
	ds_write_b64 v11, v[230:231] offset:4352
	global_load_dwordx4 v[16:19], v2, s[16:17] offset:0
	global_load_dwordx4 v[20:23], v2, s[16:17] offset:1024
	global_load_dwordx4 v[24:27], v2, s[16:17] offset:2048
	global_load_dwordx4 v[28:31], v2, s[16:17] offset:3072
	global_load_dwordx4 v[32:35], v3, s[18:19] offset:0
	global_load_dwordx4 v[36:39], v3, s[18:19] offset:1024
	global_load_dwordx4 v[40:43], v4, s[20:21]
	global_load_dword v48, v5, s[28:29]
	s_add_u32 s16, s16, 0x4000
	s_addc_u32 s17, s17, 0
	s_add_u32 s18, s18, 0x4000
	s_addc_u32 s19, s19, 0
	s_add_u32 s20, s20, s35
	s_addc_u32 s21, s21, 0
	s_add_u32 s28, s28, 4
	s_addc_u32 s29, s29, 0
	s_waitcnt lgkmcnt(0)
	s_barrier
	ds_read_b128 v[160:163], v8 offset:0
	ds_read_b128 v[176:179], v8 offset:4352
	ds_read_b128 v[164:167], v8 offset:64
	ds_read_b128 v[180:183], v8 offset:4416
	ds_read_b128 v[168:171], v8 offset:128
	ds_read_b128 v[184:187], v8 offset:4480
	ds_read_b128 v[172:175], v8 offset:192
	ds_read_b128 v[188:191], v8 offset:4544
	s_waitcnt vmcnt(16)
	v_lshlrev_b32_e32 v208, 16, v108
	v_and_b32_e32 v209, 0xffff0000, v108
	v_lshlrev_b32_e32 v210, 16, v109
	v_and_b32_e32 v211, 0xffff0000, v109
	v_lshlrev_b32_e32 v212, 16, v110
	v_and_b32_e32 v213, 0xffff0000, v110
	v_lshlrev_b32_e32 v214, 16, v111
	v_and_b32_e32 v215, 0xffff0000, v111
	s_waitcnt lgkmcnt(7)
	v_mfma_f32_16x16x32_bf16 v[208:211], v[84:87], v[160:163], v[208:211]
	s_waitcnt lgkmcnt(6)
	v_mfma_f32_16x16x32_bf16 v[212:215], v[84:87], v[176:179], v[212:215]
	s_waitcnt lgkmcnt(5)
	v_mfma_f32_16x16x32_bf16 v[208:211], v[88:91], v[164:167], v[208:211]
	s_waitcnt lgkmcnt(4)
	v_mfma_f32_16x16x32_bf16 v[212:215], v[88:91], v[180:183], v[212:215]
	s_waitcnt lgkmcnt(3)
	v_mfma_f32_16x16x32_bf16 v[208:211], v[92:95], v[168:171], v[208:211]
	s_waitcnt lgkmcnt(2)
	v_mfma_f32_16x16x32_bf16 v[212:215], v[92:95], v[184:187], v[212:215]
	s_waitcnt lgkmcnt(1)
	v_mfma_f32_16x16x32_bf16 v[208:211], v[96:99], v[172:175], v[208:211]
	s_waitcnt lgkmcnt(0)
	v_mfma_f32_16x16x32_bf16 v[212:215], v[96:99], v[188:191], v[212:215]
	s_nop 7
	v_cvt_pk_bf16_f32 v224, v208, v209
	v_cvt_pk_bf16_f32 v225, v210, v211
	v_cvt_pk_bf16_f32 v226, v212, v213
	v_cvt_pk_bf16_f32 v227, v214, v215
	ds_write_b64 v9, v[224:225]
	ds_write_b64 v9, v[226:227] offset:2304
	s_waitcnt lgkmcnt(0)
	s_barrier
	ds_read_b128 v[192:195], v10 offset:0
	ds_read_b128 v[200:203], v10 offset:2304
	ds_read_b128 v[196:199], v10 offset:64
	ds_read_b128 v[204:207], v10 offset:2368
	v_pk_mul_f32 v[216:217], v[216:217], v[116:117] op_sel_hi:[1,0]
	v_pk_mul_f32 v[218:219], v[218:219], v[116:117] op_sel_hi:[1,0]
	v_pk_mul_f32 v[220:221], v[220:221], v[116:117] op_sel_hi:[1,0]
	v_pk_mul_f32 v[222:223], v[222:223], v[116:117] op_sel_hi:[1,0]
	s_waitcnt lgkmcnt(3)
	v_mfma_f32_16x16x32_bf16 v[216:219], v[100:103], v[192:195], v[216:219]
	s_waitcnt lgkmcnt(2)
	v_mfma_f32_16x16x32_bf16 v[220:223], v[100:103], v[200:203], v[220:223]
	s_waitcnt lgkmcnt(1)
	v_mfma_f32_16x16x32_bf16 v[216:219], v[104:107], v[196:199], v[216:219]
	s_waitcnt lgkmcnt(0)
	v_mfma_f32_16x16x32_bf16 v[220:223], v[104:107], v[204:207], v[220:223]
	s_nop 7
	v_cvt_pk_bf16_f32 v228, v216, v217
	v_cvt_pk_bf16_f32 v229, v218, v219
	v_cvt_pk_bf16_f32 v230, v220, v221
	v_cvt_pk_bf16_f32 v231, v222, v223
	ds_write_b64 v11, v[228:229]
	ds_write_b64 v11, v[230:231] offset:4352
	global_load_dwordx4 v[50:53], v2, s[16:17] offset:0
	global_load_dwordx4 v[54:57], v2, s[16:17] offset:1024
	global_load_dwordx4 v[58:61], v2, s[16:17] offset:2048
	global_load_dwordx4 v[62:65], v2, s[16:17] offset:3072
	global_load_dwordx4 v[66:69], v3, s[18:19] offset:0
	global_load_dwordx4 v[70:73], v3, s[18:19] offset:1024
	global_load_dwordx4 v[74:77], v4, s[20:21]
	global_load_dword v82, v5, s[28:29]
	s_add_u32 s16, s16, 0x4000
	s_addc_u32 s17, s17, 0
	s_add_u32 s18, s18, 0x4000
	s_addc_u32 s19, s19, 0
	s_add_u32 s20, s20, s35
	s_addc_u32 s21, s21, 0
	s_add_u32 s28, s28, 4
	s_addc_u32 s29, s29, 0
	s_waitcnt lgkmcnt(0)
	s_barrier
; template <int PROBE>
; __device__ __forceinline__ void p3_scan_fast(Frame& F, const Args& a) {
;     ...
;         ScanOps opA, opB, opC;
;         SCAN_LOAD(opA, 0); SCAN_LOAD(opB, 1); if (PROBE >= 3) SCAN_LOAD(opC, 2);
;         for (int n = 0; n < NCH; n += 3) {
;             if (PROBE < 3) SCAN_LOAD(opC, n + 2); SCAN_STEP(opA, n);
;             if (PROBE < 3) SCAN_LOAD(opA, n + 3 < NCH ? n + 3 : NCH - 1); SCAN_STEP(opB, n + 1);
;             if (PROBE < 3) SCAN_LOAD(opB, n + 4 < NCH ? n + 4 : NCH - 1); SCAN_STEP(opC, n + 2);
;         }
	ds_read_b128 v[160:163], v8 offset:0
	ds_read_b128 v[176:179], v8 offset:4352
	ds_read_b128 v[164:167], v8 offset:64
	ds_read_b128 v[180:183], v8 offset:4416
	ds_read_b128 v[168:171], v8 offset:128
	ds_read_b128 v[184:187], v8 offset:4480
	ds_read_b128 v[172:175], v8 offset:192
	ds_read_b128 v[188:191], v8 offset:4544
	s_waitcnt vmcnt(16)
	v_lshlrev_b32_e32 v208, 16, v142
	v_and_b32_e32 v209, 0xffff0000, v142
	v_lshlrev_b32_e32 v210, 16, v143
	v_and_b32_e32 v211, 0xffff0000, v143
	v_lshlrev_b32_e32 v212, 16, v144
	v_and_b32_e32 v213, 0xffff0000, v144
	v_lshlrev_b32_e32 v214, 16, v145
	v_and_b32_e32 v215, 0xffff0000, v145
	s_waitcnt lgkmcnt(7)
	v_mfma_f32_16x16x32_bf16 v[208:211], v[118:121], v[160:163], v[208:211]
	s_waitcnt lgkmcnt(6)
	v_mfma_f32_16x16x32_bf16 v[212:215], v[118:121], v[176:179], v[212:215]
	s_waitcnt lgkmcnt(5)
	v_mfma_f32_16x16x32_bf16 v[208:211], v[122:125], v[164:167], v[208:211]
	s_waitcnt lgkmcnt(4)
	v_mfma_f32_16x16x32_bf16 v[212:215], v[122:125], v[180:183], v[212:215]
	s_waitcnt lgkmcnt(3)
	v_mfma_f32_16x16x32_bf16 v[208:211], v[126:129], v[168:171], v[208:211]
	s_waitcnt lgkmcnt(2)
	v_mfma_f32_16x16x32_bf16 v[212:215], v[126:129], v[184:187], v[212:215]
	s_waitcnt lgkmcnt(1)
	v_mfma_f32_16x16x32_bf16 v[208:211], v[130:133], v[172:175], v[208:211]
	s_waitcnt lgkmcnt(0)
	v_mfma_f32_16x16x32_bf16 v[212:215], v[130:133], v[188:191], v[212:215]
	s_nop 7
	v_cvt_pk_bf16_f32 v224, v208, v209
	v_cvt_pk_bf16_f32 v225, v210, v211
	v_cvt_pk_bf16_f32 v226, v212, v213
	v_cvt_pk_bf16_f32 v227, v214, v215
	ds_write_b64 v9, v[224:225]
	ds_write_b64 v9, v[226:227] offset:2304
	s_waitcnt lgkmcnt(0)
	s_barrier
	ds_read_b128 v[192:195], v10 offset:0
	ds_read_b128 v[200:203], v10 offset:2304
	ds_read_b128 v[196:199], v10 offset:64
	ds_read_b128 v[204:207], v10 offset:2368
	v_pk_mul_f32 v[216:217], v[216:217], v[150:151] op_sel_hi:[1,0]
	v_pk_mul_f32 v[218:219], v[218:219], v[150:151] op_sel_hi:[1,0]
	v_pk_mul_f32 v[220:221], v[220:221], v[150:151] op_sel_hi:[1,0]
	v_pk_mul_f32 v[222:223], v[222:223], v[150:151] op_sel_hi:[1,0]
	s_waitcnt lgkmcnt(3)
	v_mfma_f32_16x16x32_bf16 v[216:219], v[134:137], v[192:195], v[216:219]
	s_waitcnt lgkmcnt(2)
	v_mfma_f32_16x16x32_bf16 v[220:223], v[134:137], v[200:203], v[220:223]
	s_waitcnt lgkmcnt(1)
	v_mfma_f32_16x16x32_bf16 v[216:219], v[138:141], v[196:199], v[216:219]
	s_waitcnt lgkmcnt(0)
	v_mfma_f32_16x16x32_bf16 v[220:223], v[138:141], v[204:207], v[220:223]
	s_nop 7
	v_cvt_pk_bf16_f32 v228, v216, v217
	v_cvt_pk_bf16_f32 v229, v218, v219
	v_cvt_pk_bf16_f32 v230, v220, v221
	v_cvt_pk_bf16_f32 v231, v222, v223
	ds_write_b64 v11, v[228:229]
	ds_write_b64 v11, v[230:231] offset:4352
	global_load_dwordx4 v[84:87], v2, s[16:17] offset:0
	global_load_dwordx4 v[88:91], v2, s[16:17] offset:1024
	global_load_dwordx4 v[92:95], v2, s[16:17] offset:2048
	global_load_dwordx4 v[96:99], v2, s[16:17] offset:3072
	global_load_dwordx4 v[100:103], v3, s[18:19] offset:0
	global_load_dwordx4 v[104:107], v3, s[18:19] offset:1024
	global_load_dwordx4 v[108:111], v4, s[20:21]
	global_load_dword v116, v5, s[28:29]
	s_add_u32 s16, s16, 0x4000
	s_addc_u32 s17, s17, 0
	s_add_u32 s18, s18, 0x4000
	s_addc_u32 s19, s19, 0
	s_add_u32 s20, s20, s35
	s_addc_u32 s21, s21, 0
	s_add_u32 s28, s28, 4
	s_addc_u32 s29, s29, 0
	s_waitcnt lgkmcnt(0)
	s_barrier
	s_add_i32 s9, s9, 1
	s_cmp_lt_u32 s9, 8
	s_cbranch_scc1 .Lp3_vloop
	ds_read_b128 v[160:163], v8 offset:0
	ds_read_b128 v[176:179], v8 offset:4352
	ds_read_b128 v[164:167], v8 offset:64
	ds_read_b128 v[180:183], v8 offset:4416
	ds_read_b128 v[168:171], v8 offset:128
	ds_read_b128 v[184:187], v8 offset:4480
	ds_read_b128 v[172:175], v8 offset:192
	ds_read_b128 v[188:191], v8 offset:4544
	s_waitcnt vmcnt(16)
	v_lshlrev_b32_e32 v208, 16, v40
	v_and_b32_e32 v209, 0xffff0000, v40
	v_lshlrev_b32_e32 v210, 16, v41
	v_and_b32_e32 v211, 0xffff0000, v41
	v_lshlrev_b32_e32 v212, 16, v42
	v_and_b32_e32 v213, 0xffff0000, v42
	v_lshlrev_b32_e32 v214, 16, v43
	v_and_b32_e32 v215, 0xffff0000, v43
	s_waitcnt lgkmcnt(7)
	v_mfma_f32_16x16x32_bf16 v[208:211], v[16:19], v[160:163], v[208:211]
	s_waitcnt lgkmcnt(6)
	v_mfma_f32_16x16x32_bf16 v[212:215], v[16:19], v[176:179], v[212:215]
	s_waitcnt lgkmcnt(5)
	v_mfma_f32_16x16x32_bf16 v[208:211], v[20:23], v[164:167], v[208:211]
	s_waitcnt lgkmcnt(4)
	v_mfma_f32_16x16x32_bf16 v[212:215], v[20:23], v[180:183], v[212:215]
	s_waitcnt lgkmcnt(3)
	v_mfma_f32_16x16x32_bf16 v[208:211], v[24:27], v[168:171], v[208:211]
	s_waitcnt lgkmcnt(2)
	v_mfma_f32_16x16x32_bf16 v[212:215], v[24:27], v[184:187], v[212:215]
	s_waitcnt lgkmcnt(1)
	v_mfma_f32_16x16x32_bf16 v[208:211], v[28:31], v[172:175], v[208:211]
	s_waitcnt lgkmcnt(0)
	v_mfma_f32_16x16x32_bf16 v[212:215], v[28:31], v[188:191], v[212:215]
	s_nop 7
	v_cvt_pk_bf16_f32 v224, v208, v209
	v_cvt_pk_bf16_f32 v225, v210, v211
	v_cvt_pk_bf16_f32 v226, v212, v213
	v_cvt_pk_bf16_f32 v227, v214, v215
	ds_write_b64 v9, v[224:225]
	ds_write_b64 v9, v[226:227] offset:2304
	s_waitcnt lgkmcnt(0)
	s_barrier
	ds_read_b128 v[192:195], v10 offset:0
	ds_read_b128 v[200:203], v10 offset:2304
	ds_read_b128 v[196:199], v10 offset:64
	ds_read_b128 v[204:207], v10 offset:2368
	v_pk_mul_f32 v[216:217], v[216:217], v[48:49] op_sel_hi:[1,0]
	v_pk_mul_f32 v[218:219], v[218:219], v[48:49] op_sel_hi:[1,0]
	v_pk_mul_f32 v[220:221], v[220:221], v[48:49] op_sel_hi:[1,0]
	v_pk_mul_f32 v[222:223], v[222:223], v[48:49] op_sel_hi:[1,0]
	s_waitcnt lgkmcnt(3)
	v_mfma_f32_16x16x32_bf16 v[216:219], v[32:35], v[192:195], v[216:219]
	s_waitcnt lgkmcnt(2)
	v_mfma_f32_16x16x32_bf16 v[220:223], v[32:35], v[200:203], v[220:223]
	s_waitcnt lgkmcnt(1)
	v_mfma_f32_16x16x32_bf16 v[216:219], v[36:39], v[196:199], v[216:219]
	s_waitcnt lgkmcnt(0)
	v_mfma_f32_16x16x32_bf16 v[220:223], v[36:39], v[204:207], v[220:223]
	s_nop 7
	v_cvt_pk_bf16_f32 v228, v216, v217
	v_cvt_pk_bf16_f32 v229, v218, v219
	v_cvt_pk_bf16_f32 v230, v220, v221
	v_cvt_pk_bf16_f32 v231, v222, v223
	ds_write_b64 v11, v[228:229]
	ds_write_b64 v11, v[230:231] offset:4352
	global_load_dwordx4 v[118:121], v2, s[16:17] offset:0
	global_load_dwordx4 v[122:125], v2, s[16:17] offset:1024
	global_load_dwordx4 v[126:129], v2, s[16:17] offset:2048
	global_load_dwordx4 v[130:133], v2, s[16:17] offset:3072
	global_load_dwordx4 v[134:137], v3, s[18:19] offset:0
	global_load_dwordx4 v[138:141], v3, s[18:19] offset:1024
	global_load_dwordx4 v[142:145], v4, s[20:21]
	global_load_dword v150, v5, s[28:29]
	s_add_u32 s16, s16, 0x4000
	s_addc_u32 s17, s17, 0
	s_add_u32 s18, s18, 0x4000
	s_addc_u32 s19, s19, 0
	s_add_u32 s20, s20, s35
	s_addc_u32 s21, s21, 0
	s_add_u32 s28, s28, 4
	s_addc_u32 s29, s29, 0
	s_waitcnt lgkmcnt(0)
	s_barrier
	s_branch .Lp3_done
; template <int PROBE>
; __device__ __forceinline__ void p3_scan_fast(Frame& F, const Args& a) {
;     ...
;         ScanOps opA, opB, opC;
;         SCAN_LOAD(opA, 0); SCAN_LOAD(opB, 1); if (PROBE >= 3) SCAN_LOAD(opC, 2);
;         for (int n = 0; n < NCH; n += 3) {
;             if (PROBE < 3) SCAN_LOAD(opC, n + 2); SCAN_STEP(opA, n);
;             if (PROBE < 3) SCAN_LOAD(opA, n + 3 < NCH ? n + 3 : NCH - 1); SCAN_STEP(opB, n + 1);
;             if (PROBE < 3) SCAN_LOAD(opB, n + 4 < NCH ? n + 4 : NCH - 1); SCAN_STEP(opC, n + 2);
.Lp3_owave:
	global_load_dwordx4 v[16:19], v2, s[16:17] offset:0
	global_load_dwordx4 v[20:23], v2, s[16:17] offset:1024
	global_load_dwordx4 v[24:27], v2, s[16:17] offset:2048
	global_load_dwordx4 v[28:31], v2, s[16:17] offset:3072
	global_load_dwordx4 v[32:35], v3, s[18:19] offset:0
	global_load_dwordx4 v[36:39], v3, s[18:19] offset:1024
	global_load_dwordx4 v[40:43], v4, s[20:21]
	global_load_dwordx4 v[44:47], v4, s[20:21] offset:1024
	global_load_dword v48, v5, s[28:29]
	s_add_u32 s16, s16, 0x4000
	s_addc_u32 s17, s17, 0
	s_add_u32 s18, s18, 0x4000
	s_addc_u32 s19, s19, 0
	s_add_u32 s20, s20, s35
	s_addc_u32 s21, s21, 0
	s_add_u32 s28, s28, 4
	s_addc_u32 s29, s29, 0
	global_store_dword v6, v5, s[30:31]
	global_store_dword v6, v5, s[30:31]
	global_store_dword v6, v5, s[30:31]
	global_store_dword v6, v5, s[30:31]
	global_load_dwordx4 v[50:53], v2, s[16:17] offset:0
	global_load_dwordx4 v[54:57], v2, s[16:17] offset:1024
	global_load_dwordx4 v[58:61], v2, s[16:17] offset:2048
	global_load_dwordx4 v[62:65], v2, s[16:17] offset:3072
	global_load_dwordx4 v[66:69], v3, s[18:19] offset:0
	global_load_dwordx4 v[70:73], v3, s[18:19] offset:1024
	global_load_dwordx4 v[74:77], v4, s[20:21]
	global_load_dwordx4 v[78:81], v4, s[20:21] offset:1024
	global_load_dword v82, v5, s[28:29]
	s_add_u32 s16, s16, 0x4000
	s_addc_u32 s17, s17, 0
	s_add_u32 s18, s18, 0x4000
	s_addc_u32 s19, s19, 0
	s_add_u32 s20, s20, s35
	s_addc_u32 s21, s21, 0
	s_add_u32 s28, s28, 4
	s_addc_u32 s29, s29, 0
	global_store_dword v6, v5, s[30:31]
	global_store_dword v6, v5, s[30:31]
	global_store_dword v6, v5, s[30:31]
	global_store_dword v6, v5, s[30:31]
	global_load_dwordx4 v[84:87], v2, s[16:17] offset:0
	global_load_dwordx4 v[88:91], v2, s[16:17] offset:1024
	global_load_dwordx4 v[92:95], v2, s[16:17] offset:2048
	global_load_dwordx4 v[96:99], v2, s[16:17] offset:3072
	global_load_dwordx4 v[100:103], v3, s[18:19] offset:0
	global_load_dwordx4 v[104:107], v3, s[18:19] offset:1024
	global_load_dwordx4 v[108:111], v4, s[20:21]
	global_load_dwordx4 v[112:115], v4, s[20:21] offset:1024
	global_load_dword v116, v5, s[28:29]
	s_add_u32 s16, s16, 0x4000
	s_addc_u32 s17, s17, 0
	s_add_u32 s18, s18, 0x4000
	s_addc_u32 s19, s19, 0
	s_add_u32 s20, s20, s35
	s_addc_u32 s21, s21, 0
	s_add_u32 s28, s28, 4
	s_addc_u32 s29, s29, 0
	s_mov_b32 s9, 0
.Lp3_oloop:
	ds_read_b128 v[160:163], v8 offset:0
	ds_read_b128 v[176:179], v8 offset:4352
	ds_read_b128 v[164:167], v8 offset:64
	ds_read_b128 v[180:183], v8 offset:4416
	ds_read_b128 v[168:171], v8 offset:128
	ds_read_b128 v[184:187], v8 offset:4480
	ds_read_b128 v[172:175], v8 offset:192
	ds_read_b128 v[188:191], v8 offset:4544
	v_mfma_f32_16x16x32_bf16 v[208:211], v[142:145], v[192:195], v[208:211]
	v_mfma_f32_16x16x32_bf16 v[208:211], v[146:149], v[196:199], v[208:211]
	v_mfma_f32_16x16x32_bf16 v[212:215], v[142:145], v[200:203], v[212:215]
	v_mfma_f32_16x16x32_bf16 v[212:215], v[146:149], v[204:207], v[212:215]
	s_nop 7
	v_mov_b32_dpp v232, v208 quad_perm:[1,0,3,2] row_mask:0xf bank_mask:0xf
	v_mov_b32_dpp v233, v212 quad_perm:[1,0,3,2] row_mask:0xf bank_mask:0xf
	v_cndmask_b32_e64 v236, v233, v208, s[40:41]
	v_cndmask_b32_e64 v237, v212, v232, s[40:41]
	v_cvt_pk_bf16_f32 v240, v236, v237
	v_mov_b32_dpp v234, v209 quad_perm:[1,0,3,2] row_mask:0xf bank_mask:0xf
	v_mov_b32_dpp v235, v213 quad_perm:[1,0,3,2] row_mask:0xf bank_mask:0xf
	v_cndmask_b32_e64 v236, v235, v209, s[40:41]
	v_cndmask_b32_e64 v237, v213, v234, s[40:41]
	v_cvt_pk_bf16_f32 v241, v236, v237
	v_mov_b32_dpp v232, v210 quad_perm:[1,0,3,2] row_mask:0xf bank_mask:0xf
	v_mov_b32_dpp v233, v214 quad_perm:[1,0,3,2] row_mask:0xf bank_mask:0xf
	v_cndmask_b32_e64 v236, v233, v210, s[40:41]
	v_cndmask_b32_e64 v237, v214, v232, s[40:41]
	v_cvt_pk_bf16_f32 v242, v236, v237
	v_mov_b32_dpp v234, v211 quad_perm:[1,0,3,2] row_mask:0xf bank_mask:0xf
	v_mov_b32_dpp v235, v215 quad_perm:[1,0,3,2] row_mask:0xf bank_mask:0xf
	v_cndmask_b32_e64 v236, v235, v211, s[40:41]
	v_cndmask_b32_e64 v237, v215, v234, s[40:41]
	v_cvt_pk_bf16_f32 v243, v236, v237
	global_store_dword v6, v240, s[30:31] offset:-4096
	global_store_dword v6, v241, s[30:31] offset:0
	global_store_dword v7, v242, s[30:31] offset:-4096
	global_store_dword v7, v243, s[30:31] offset:0
	s_add_u32 s44, s30, 0x40000
	s_addc_u32 s45, s31, 0
	s_cmp_eq_u32 s9, 0
	s_cselect_b64 s[30:31], s[30:31], s[44:45]
	s_waitcnt vmcnt(30)
	s_waitcnt lgkmcnt(7)
	v_mfma_f32_16x16x32_bf16 v[208:211], v[16:19], v[160:163], 0
	s_waitcnt lgkmcnt(6)
	v_mfma_f32_16x16x32_bf16 v[212:215], v[16:19], v[176:179], 0
	s_waitcnt lgkmcnt(5)
	v_mfma_f32_16x16x32_bf16 v[208:211], v[20:23], v[164:167], v[208:211]
	s_waitcnt lgkmcnt(4)
	v_mfma_f32_16x16x32_bf16 v[212:215], v[20:23], v[180:183], v[212:215]
	s_waitcnt lgkmcnt(3)
	v_mfma_f32_16x16x32_bf16 v[208:211], v[24:27], v[168:171], v[208:211]
	s_waitcnt lgkmcnt(2)
	v_mfma_f32_16x16x32_bf16 v[212:215], v[24:27], v[184:187], v[212:215]
	s_waitcnt lgkmcnt(1)
	v_mfma_f32_16x16x32_bf16 v[208:211], v[28:31], v[172:175], v[208:211]
	s_waitcnt lgkmcnt(0)
	v_mfma_f32_16x16x32_bf16 v[212:215], v[28:31], v[188:191], v[212:215]
	s_barrier
	ds_read_b128 v[192:195], v10 offset:0
	ds_read_b128 v[200:203], v10 offset:2304
	ds_read_b128 v[196:199], v10 offset:64
	ds_read_b128 v[204:207], v10 offset:2368
	v_pk_mul_f32 v[216:217], v[216:217], v[48:49] op_sel_hi:[1,0]
	v_pk_mul_f32 v[218:219], v[218:219], v[48:49] op_sel_hi:[1,0]
	v_pk_mul_f32 v[220:221], v[220:221], v[48:49] op_sel_hi:[1,0]
	v_pk_mul_f32 v[222:223], v[222:223], v[48:49] op_sel_hi:[1,0]
	s_waitcnt lgkmcnt(3)
	v_mfma_f32_16x16x32_bf16 v[216:219], v[32:35], v[192:195], v[216:219]
	s_waitcnt lgkmcnt(2)
	v_mfma_f32_16x16x32_bf16 v[220:223], v[32:35], v[200:203], v[220:223]
	s_waitcnt lgkmcnt(1)
	v_mfma_f32_16x16x32_bf16 v[216:219], v[36:39], v[196:199], v[216:219]
	s_waitcnt lgkmcnt(0)
	v_mfma_f32_16x16x32_bf16 v[220:223], v[36:39], v[204:207], v[220:223]
	s_nop 7
	v_cvt_pk_bf16_f32 v228, v216, v217
	v_cvt_pk_bf16_f32 v229, v218, v219
	v_cvt_pk_bf16_f32 v230, v220, v221
	v_cvt_pk_bf16_f32 v231, v222, v223
	ds_write_b64 v11, v[228:229]
	ds_write_b64 v11, v[230:231] offset:4352
	global_load_dwordx4 v[118:121], v2, s[16:17] offset:0
	global_load_dwordx4 v[122:125], v2, s[16:17] offset:1024
	global_load_dwordx4 v[126:129], v2, s[16:17] offset:2048
	global_load_dwordx4 v[130:133], v2, s[16:17] offset:3072
	global_load_dwordx4 v[134:137], v3, s[18:19] offset:0
	global_load_dwordx4 v[138:141], v3, s[18:19] offset:1024
	global_load_dwordx4 v[142:145], v4, s[20:21]
	global_load_dwordx4 v[146:149], v4, s[20:21] offset:1024
	global_load_dword v150, v5, s[28:29]
	s_add_u32 s16, s16, 0x4000
	s_addc_u32 s17, s17, 0
	s_add_u32 s18, s18, 0x4000
	s_addc_u32 s19, s19, 0
	s_add_u32 s20, s20, s35
	s_addc_u32 s21, s21, 0
	s_add_u32 s28, s28, 4
	s_addc_u32 s29, s29, 0
	s_waitcnt lgkmcnt(0)
	s_barrier
	ds_read_b128 v[160:163], v8 offset:0
	ds_read_b128 v[176:179], v8 offset:4352
	ds_read_b128 v[164:167], v8 offset:64
	ds_read_b128 v[180:183], v8 offset:4416
	ds_read_b128 v[168:171], v8 offset:128
	ds_read_b128 v[184:187], v8 offset:4480
	ds_read_b128 v[172:175], v8 offset:192
	ds_read_b128 v[188:191], v8 offset:4544
	v_mfma_f32_16x16x32_bf16 v[208:211], v[40:43], v[192:195], v[208:211]
	v_mfma_f32_16x16x32_bf16 v[208:211], v[44:47], v[196:199], v[208:211]
	v_mfma_f32_16x16x32_bf16 v[212:215], v[40:43], v[200:203], v[212:215]
	v_mfma_f32_16x16x32_bf16 v[212:215], v[44:47], v[204:207], v[212:215]
	s_nop 7
	v_mov_b32_dpp v232, v208 quad_perm:[1,0,3,2] row_mask:0xf bank_mask:0xf
	v_mov_b32_dpp v233, v212 quad_perm:[1,0,3,2] row_mask:0xf bank_mask:0xf
	v_cndmask_b32_e64 v236, v233, v208, s[40:41]
	v_cndmask_b32_e64 v237, v212, v232, s[40:41]
	v_cvt_pk_bf16_f32 v240, v236, v237
	v_mov_b32_dpp v234, v209 quad_perm:[1,0,3,2] row_mask:0xf bank_mask:0xf
	v_mov_b32_dpp v235, v213 quad_perm:[1,0,3,2] row_mask:0xf bank_mask:0xf
	v_cndmask_b32_e64 v236, v235, v209, s[40:41]
	v_cndmask_b32_e64 v237, v213, v234, s[40:41]
	v_cvt_pk_bf16_f32 v241, v236, v237
	v_mov_b32_dpp v232, v210 quad_perm:[1,0,3,2] row_mask:0xf bank_mask:0xf
	v_mov_b32_dpp v233, v214 quad_perm:[1,0,3,2] row_mask:0xf bank_mask:0xf
	v_cndmask_b32_e64 v236, v233, v210, s[40:41]
	v_cndmask_b32_e64 v237, v214, v232, s[40:41]
	v_cvt_pk_bf16_f32 v242, v236, v237
	v_mov_b32_dpp v234, v211 quad_perm:[1,0,3,2] row_mask:0xf bank_mask:0xf
	v_mov_b32_dpp v235, v215 quad_perm:[1,0,3,2] row_mask:0xf bank_mask:0xf
	v_cndmask_b32_e64 v236, v235, v211, s[40:41]
	v_cndmask_b32_e64 v237, v215, v234, s[40:41]
	v_cvt_pk_bf16_f32 v243, v236, v237
	global_store_dword v6, v240, s[30:31] offset:-4096
	global_store_dword v6, v241, s[30:31] offset:0
	global_store_dword v7, v242, s[30:31] offset:-4096
	global_store_dword v7, v243, s[30:31] offset:0
	s_add_u32 s44, s30, 0x40000
	s_addc_u32 s45, s31, 0
	s_cmp_eq_u32 s9, 0
	s_cselect_b64 s[30:31], s[42:43], s[44:45]
	s_waitcnt vmcnt(30)
	s_waitcnt lgkmcnt(7)
	v_mfma_f32_16x16x32_bf16 v[208:211], v[50:53], v[160:163], 0
	s_waitcnt lgkmcnt(6)
	v_mfma_f32_16x16x32_bf16 v[212:215], v[50:53], v[176:179], 0
	s_waitcnt lgkmcnt(5)
	v_mfma_f32_16x16x32_bf16 v[208:211], v[54:57], v[164:167], v[208:211]
	s_waitcnt lgkmcnt(4)
	v_mfma_f32_16x16x32_bf16 v[212:215], v[54:57], v[180:183], v[212:215]
	s_waitcnt lgkmcnt(3)
	v_mfma_f32_16x16x32_bf16 v[208:211], v[58:61], v[168:171], v[208:211]
	s_waitcnt lgkmcnt(2)
	v_mfma_f32_16x16x32_bf16 v[212:215], v[58:61], v[184:187], v[212:215]
	s_waitcnt lgkmcnt(1)
	v_mfma_f32_16x16x32_bf16 v[208:211], v[62:65], v[172:175], v[208:211]
	s_waitcnt lgkmcnt(0)
	v_mfma_f32_16x16x32_bf16 v[212:215], v[62:65], v[188:191], v[212:215]
	s_barrier
	ds_read_b128 v[192:195], v10 offset:0
	ds_read_b128 v[200:203], v10 offset:2304
	ds_read_b128 v[196:199], v10 offset:64
	ds_read_b128 v[204:207], v10 offset:2368
	v_pk_mul_f32 v[216:217], v[216:217], v[82:83] op_sel_hi:[1,0]
	v_pk_mul_f32 v[218:219], v[218:219], v[82:83] op_sel_hi:[1,0]
	v_pk_mul_f32 v[220:221], v[220:221], v[82:83] op_sel_hi:[1,0]
	v_pk_mul_f32 v[222:223], v[222:223], v[82:83] op_sel_hi:[1,0]
	s_waitcnt lgkmcnt(3)
	v_mfma_f32_16x16x32_bf16 v[216:219], v[66:69], v[192:195], v[216:219]
	s_waitcnt lgkmcnt(2)
	v_mfma_f32_16x16x32_bf16 v[220:223], v[66:69], v[200:203], v[220:223]
	s_waitcnt lgkmcnt(1)
	v_mfma_f32_16x16x32_bf16 v[216:219], v[70:73], v[196:199], v[216:219]
	s_waitcnt lgkmcnt(0)
	v_mfma_f32_16x16x32_bf16 v[220:223], v[70:73], v[204:207], v[220:223]
	s_nop 7
	v_cvt_pk_bf16_f32 v228, v216, v217
	v_cvt_pk_bf16_f32 v229, v218, v219
	v_cvt_pk_bf16_f32 v230, v220, v221
	v_cvt_pk_bf16_f32 v231, v222, v223
	ds_write_b64 v11, v[228:229]
	ds_write_b64 v11, v[230:231] offset:4352
	global_load_dwordx4 v[16:19], v2, s[16:17] offset:0
	global_load_dwordx4 v[20:23], v2, s[16:17] offset:1024
	global_load_dwordx4 v[24:27], v2, s[16:17] offset:2048
	global_load_dwordx4 v[28:31], v2, s[16:17] offset:3072
	global_load_dwordx4 v[32:35], v3, s[18:19] offset:0
	global_load_dwordx4 v[36:39], v3, s[18:19] offset:1024
	global_load_dwordx4 v[40:43], v4, s[20:21]
	global_load_dwordx4 v[44:47], v4, s[20:21] offset:1024
	global_load_dword v48, v5, s[28:29]
	s_add_u32 s16, s16, 0x4000
	s_addc_u32 s17, s17, 0
	s_add_u32 s18, s18, 0x4000
	s_addc_u32 s19, s19, 0
	s_add_u32 s20, s20, s35
	s_addc_u32 s21, s21, 0
	s_add_u32 s28, s28, 4
	s_addc_u32 s29, s29, 0
	s_waitcnt lgkmcnt(0)
	s_barrier
	ds_read_b128 v[160:163], v8 offset:0
	ds_read_b128 v[176:179], v8 offset:4352
	ds_read_b128 v[164:167], v8 offset:64
	ds_read_b128 v[180:183], v8 offset:4416
	ds_read_b128 v[168:171], v8 offset:128
	ds_read_b128 v[184:187], v8 offset:4480
	ds_read_b128 v[172:175], v8 offset:192
	ds_read_b128 v[188:191], v8 offset:4544
	v_mfma_f32_16x16x32_bf16 v[208:211], v[74:77], v[192:195], v[208:211]
	v_mfma_f32_16x16x32_bf16 v[208:211], v[78:81], v[196:199], v[208:211]
	v_mfma_f32_16x16x32_bf16 v[212:215], v[74:77], v[200:203], v[212:215]
	v_mfma_f32_16x16x32_bf16 v[212:215], v[78:81], v[204:207], v[212:215]
	s_nop 7
	v_mov_b32_dpp v232, v208 quad_perm:[1,0,3,2] row_mask:0xf bank_mask:0xf
	v_mov_b32_dpp v233, v212 quad_perm:[1,0,3,2] row_mask:0xf bank_mask:0xf
	v_cndmask_b32_e64 v236, v233, v208, s[40:41]
	v_cndmask_b32_e64 v237, v212, v232, s[40:41]
	v_cvt_pk_bf16_f32 v240, v236, v237
	v_mov_b32_dpp v234, v209 quad_perm:[1,0,3,2] row_mask:0xf bank_mask:0xf
	v_mov_b32_dpp v235, v213 quad_perm:[1,0,3,2] row_mask:0xf bank_mask:0xf
	v_cndmask_b32_e64 v236, v235, v209, s[40:41]
	v_cndmask_b32_e64 v237, v213, v234, s[40:41]
	v_cvt_pk_bf16_f32 v241, v236, v237
	v_mov_b32_dpp v232, v210 quad_perm:[1,0,3,2] row_mask:0xf bank_mask:0xf
	v_mov_b32_dpp v233, v214 quad_perm:[1,0,3,2] row_mask:0xf bank_mask:0xf
	v_cndmask_b32_e64 v236, v233, v210, s[40:41]
	v_cndmask_b32_e64 v237, v214, v232, s[40:41]
	v_cvt_pk_bf16_f32 v242, v236, v237
	v_mov_b32_dpp v234, v211 quad_perm:[1,0,3,2] row_mask:0xf bank_mask:0xf
	v_mov_b32_dpp v235, v215 quad_perm:[1,0,3,2] row_mask:0xf bank_mask:0xf
	v_cndmask_b32_e64 v236, v235, v211, s[40:41]
	v_cndmask_b32_e64 v237, v215, v234, s[40:41]
	v_cvt_pk_bf16_f32 v243, v236, v237
	global_store_dword v6, v240, s[30:31] offset:-4096
	global_store_dword v6, v241, s[30:31] offset:0
	global_store_dword v7, v242, s[30:31] offset:-4096
	global_store_dword v7, v243, s[30:31] offset:0
	s_add_u32 s44, s30, 0x40000
	s_addc_u32 s45, s31, 0
	s_mov_b64 s[30:31], s[44:45]
	s_waitcnt vmcnt(30)
	s_waitcnt lgkmcnt(7)
	v_mfma_f32_16x16x32_bf16 v[208:211], v[84:87], v[160:163], 0
	s_waitcnt lgkmcnt(6)
	v_mfma_f32_16x16x32_bf16 v[212:215], v[84:87], v[176:179], 0
	s_waitcnt lgkmcnt(5)
	v_mfma_f32_16x16x32_bf16 v[208:211], v[88:91], v[164:167], v[208:211]
	s_waitcnt lgkmcnt(4)
	v_mfma_f32_16x16x32_bf16 v[212:215], v[88:91], v[180:183], v[212:215]
	s_waitcnt lgkmcnt(3)
	v_mfma_f32_16x16x32_bf16 v[208:211], v[92:95], v[168:171], v[208:211]
	s_waitcnt lgkmcnt(2)
	v_mfma_f32_16x16x32_bf16 v[212:215], v[92:95], v[184:187], v[212:215]
	s_waitcnt lgkmcnt(1)
	v_mfma_f32_16x16x32_bf16 v[208:211], v[96:99], v[172:175], v[208:211]
	s_waitcnt lgkmcnt(0)
	v_mfma_f32_16x16x32_bf16 v[212:215], v[96:99], v[188:191], v[212:215]
	s_barrier
	ds_read_b128 v[192:195], v10 offset:0
	ds_read_b128 v[200:203], v10 offset:2304
	ds_read_b128 v[196:199], v10 offset:64
	ds_read_b128 v[204:207], v10 offset:2368
	v_pk_mul_f32 v[216:217], v[216:217], v[116:117] op_sel_hi:[1,0]
	v_pk_mul_f32 v[218:219], v[218:219], v[116:117] op_sel_hi:[1,0]
	v_pk_mul_f32 v[220:221], v[220:221], v[116:117] op_sel_hi:[1,0]
	v_pk_mul_f32 v[222:223], v[222:223], v[116:117] op_sel_hi:[1,0]
	s_waitcnt lgkmcnt(3)
	v_mfma_f32_16x16x32_bf16 v[216:219], v[100:103], v[192:195], v[216:219]
	s_waitcnt lgkmcnt(2)
	v_mfma_f32_16x16x32_bf16 v[220:223], v[100:103], v[200:203], v[220:223]
	s_waitcnt lgkmcnt(1)
	v_mfma_f32_16x16x32_bf16 v[216:219], v[104:107], v[196:199], v[216:219]
	s_waitcnt lgkmcnt(0)
	v_mfma_f32_16x16x32_bf16 v[220:223], v[104:107], v[204:207], v[220:223]
	s_nop 7
	v_cvt_pk_bf16_f32 v228, v216, v217
	v_cvt_pk_bf16_f32 v229, v218, v219
	v_cvt_pk_bf16_f32 v230, v220, v221
	v_cvt_pk_bf16_f32 v231, v222, v223
	ds_write_b64 v11, v[228:229]
	ds_write_b64 v11, v[230:231] offset:4352
	global_load_dwordx4 v[50:53], v2, s[16:17] offset:0
	global_load_dwordx4 v[54:57], v2, s[16:17] offset:1024
	global_load_dwordx4 v[58:61], v2, s[16:17] offset:2048
	global_load_dwordx4 v[62:65], v2, s[16:17] offset:3072
	global_load_dwordx4 v[66:69], v3, s[18:19] offset:0
	global_load_dwordx4 v[70:73], v3, s[18:19] offset:1024
	global_load_dwordx4 v[74:77], v4, s[20:21]
	global_load_dwordx4 v[78:81], v4, s[20:21] offset:1024
	global_load_dword v82, v5, s[28:29]
	s_add_u32 s16, s16, 0x4000
	s_addc_u32 s17, s17, 0
	s_add_u32 s18, s18, 0x4000
	s_addc_u32 s19, s19, 0
	s_add_u32 s20, s20, s35
	s_addc_u32 s21, s21, 0
	s_add_u32 s28, s28, 4
	s_addc_u32 s29, s29, 0
	s_waitcnt lgkmcnt(0)
	s_barrier
	ds_read_b128 v[160:163], v8 offset:0
	ds_read_b128 v[176:179], v8 offset:4352
	ds_read_b128 v[164:167], v8 offset:64
	ds_read_b128 v[180:183], v8 offset:4416
	ds_read_b128 v[168:171], v8 offset:128
	ds_read_b128 v[184:187], v8 offset:4480
	ds_read_b128 v[172:175], v8 offset:192
	ds_read_b128 v[188:191], v8 offset:4544
	v_mfma_f32_16x16x32_bf16 v[208:211], v[108:111], v[192:195], v[208:211]
	v_mfma_f32_16x16x32_bf16 v[208:211], v[112:115], v[196:199], v[208:211]
	v_mfma_f32_16x16x32_bf16 v[212:215], v[108:111], v[200:203], v[212:215]
	v_mfma_f32_16x16x32_bf16 v[212:215], v[112:115], v[204:207], v[212:215]
	s_nop 7
	v_mov_b32_dpp v232, v208 quad_perm:[1,0,3,2] row_mask:0xf bank_mask:0xf
	v_mov_b32_dpp v233, v212 quad_perm:[1,0,3,2] row_mask:0xf bank_mask:0xf
	v_cndmask_b32_e64 v236, v233, v208, s[40:41]
	v_cndmask_b32_e64 v237, v212, v232, s[40:41]
	v_cvt_pk_bf16_f32 v240, v236, v237
	v_mov_b32_dpp v234, v209 quad_perm:[1,0,3,2] row_mask:0xf bank_mask:0xf
	v_mov_b32_dpp v235, v213 quad_perm:[1,0,3,2] row_mask:0xf bank_mask:0xf
	v_cndmask_b32_e64 v236, v235, v209, s[40:41]
	v_cndmask_b32_e64 v237, v213, v234, s[40:41]
	v_cvt_pk_bf16_f32 v241, v236, v237
	v_mov_b32_dpp v232, v210 quad_perm:[1,0,3,2] row_mask:0xf bank_mask:0xf
	v_mov_b32_dpp v233, v214 quad_perm:[1,0,3,2] row_mask:0xf bank_mask:0xf
	v_cndmask_b32_e64 v236, v233, v210, s[40:41]
	v_cndmask_b32_e64 v237, v214, v232, s[40:41]
	v_cvt_pk_bf16_f32 v242, v236, v237
	v_mov_b32_dpp v234, v211 quad_perm:[1,0,3,2] row_mask:0xf bank_mask:0xf
	v_mov_b32_dpp v235, v215 quad_perm:[1,0,3,2] row_mask:0xf bank_mask:0xf
	v_cndmask_b32_e64 v236, v235, v211, s[40:41]
	v_cndmask_b32_e64 v237, v215, v234, s[40:41]
	v_cvt_pk_bf16_f32 v243, v236, v237
	global_store_dword v6, v240, s[30:31] offset:-4096
	global_store_dword v6, v241, s[30:31] offset:0
	global_store_dword v7, v242, s[30:31] offset:-4096
	global_store_dword v7, v243, s[30:31] offset:0
	s_add_u32 s44, s30, 0x40000
	s_addc_u32 s45, s31, 0
	s_mov_b64 s[30:31], s[44:45]
	s_waitcnt vmcnt(30)
	s_waitcnt lgkmcnt(7)
	v_mfma_f32_16x16x32_bf16 v[208:211], v[118:121], v[160:163], 0
	s_waitcnt lgkmcnt(6)
	v_mfma_f32_16x16x32_bf16 v[212:215], v[118:121], v[176:179], 0
	s_waitcnt lgkmcnt(5)
	v_mfma_f32_16x16x32_bf16 v[208:211], v[122:125], v[164:167], v[208:211]
	s_waitcnt lgkmcnt(4)
	v_mfma_f32_16x16x32_bf16 v[212:215], v[122:125], v[180:183], v[212:215]
	s_waitcnt lgkmcnt(3)
	v_mfma_f32_16x16x32_bf16 v[208:211], v[126:129], v[168:171], v[208:211]
	s_waitcnt lgkmcnt(2)
	v_mfma_f32_16x16x32_bf16 v[212:215], v[126:129], v[184:187], v[212:215]
	s_waitcnt lgkmcnt(1)
	v_mfma_f32_16x16x32_bf16 v[208:211], v[130:133], v[172:175], v[208:211]
	s_waitcnt lgkmcnt(0)
	v_mfma_f32_16x16x32_bf16 v[212:215], v[130:133], v[188:191], v[212:215]
	s_barrier
	ds_read_b128 v[192:195], v10 offset:0
	ds_read_b128 v[200:203], v10 offset:2304
	ds_read_b128 v[196:199], v10 offset:64
	ds_read_b128 v[204:207], v10 offset:2368
	v_pk_mul_f32 v[216:217], v[216:217], v[150:151] op_sel_hi:[1,0]
	v_pk_mul_f32 v[218:219], v[218:219], v[150:151] op_sel_hi:[1,0]
	v_pk_mul_f32 v[220:221], v[220:221], v[150:151] op_sel_hi:[1,0]
	v_pk_mul_f32 v[222:223], v[222:223], v[150:151] op_sel_hi:[1,0]
	s_waitcnt lgkmcnt(3)
	v_mfma_f32_16x16x32_bf16 v[216:219], v[134:137], v[192:195], v[216:219]
	s_waitcnt lgkmcnt(2)
	v_mfma_f32_16x16x32_bf16 v[220:223], v[134:137], v[200:203], v[220:223]
	s_waitcnt lgkmcnt(1)
	v_mfma_f32_16x16x32_bf16 v[216:219], v[138:141], v[196:199], v[216:219]
	s_waitcnt lgkmcnt(0)
	v_mfma_f32_16x16x32_bf16 v[220:223], v[138:141], v[204:207], v[220:223]
	s_nop 7
	v_cvt_pk_bf16_f32 v228, v216, v217
	v_cvt_pk_bf16_f32 v229, v218, v219
	v_cvt_pk_bf16_f32 v230, v220, v221
	v_cvt_pk_bf16_f32 v231, v222, v223
	ds_write_b64 v11, v[228:229]
	ds_write_b64 v11, v[230:231] offset:4352
	global_load_dwordx4 v[84:87], v2, s[16:17] offset:0
	global_load_dwordx4 v[88:91], v2, s[16:17] offset:1024
	global_load_dwordx4 v[92:95], v2, s[16:17] offset:2048
	global_load_dwordx4 v[96:99], v2, s[16:17] offset:3072
	global_load_dwordx4 v[100:103], v3, s[18:19] offset:0
	global_load_dwordx4 v[104:107], v3, s[18:19] offset:1024
	global_load_dwordx4 v[108:111], v4, s[20:21]
	global_load_dwordx4 v[112:115], v4, s[20:21] offset:1024
	global_load_dword v116, v5, s[28:29]
	s_add_u32 s16, s16, 0x4000
	s_addc_u32 s17, s17, 0
	s_add_u32 s18, s18, 0x4000
	s_addc_u32 s19, s19, 0
	s_add_u32 s20, s20, s35
	s_addc_u32 s21, s21, 0
	s_add_u32 s28, s28, 4
	s_addc_u32 s29, s29, 0
	s_waitcnt lgkmcnt(0)
	s_barrier
	s_add_i32 s9, s9, 1
	s_cmp_lt_u32 s9, 8
	s_cbranch_scc1 .Lp3_oloop
	ds_read_b128 v[160:163], v8 offset:0
	ds_read_b128 v[176:179], v8 offset:4352
	ds_read_b128 v[164:167], v8 offset:64
	ds_read_b128 v[180:183], v8 offset:4416
	ds_read_b128 v[168:171], v8 offset:128
	ds_read_b128 v[184:187], v8 offset:4480
	ds_read_b128 v[172:175], v8 offset:192
	ds_read_b128 v[188:191], v8 offset:4544
	v_mfma_f32_16x16x32_bf16 v[208:211], v[142:145], v[192:195], v[208:211]
	v_mfma_f32_16x16x32_bf16 v[208:211], v[146:149], v[196:199], v[208:211]
	v_mfma_f32_16x16x32_bf16 v[212:215], v[142:145], v[200:203], v[212:215]
	v_mfma_f32_16x16x32_bf16 v[212:215], v[146:149], v[204:207], v[212:215]
	s_nop 7
	v_mov_b32_dpp v232, v208 quad_perm:[1,0,3,2] row_mask:0xf bank_mask:0xf
	v_mov_b32_dpp v233, v212 quad_perm:[1,0,3,2] row_mask:0xf bank_mask:0xf
	v_cndmask_b32_e64 v236, v233, v208, s[40:41]
	v_cndmask_b32_e64 v237, v212, v232, s[40:41]
	v_cvt_pk_bf16_f32 v240, v236, v237
	v_mov_b32_dpp v234, v209 quad_perm:[1,0,3,2] row_mask:0xf bank_mask:0xf
	v_mov_b32_dpp v235, v213 quad_perm:[1,0,3,2] row_mask:0xf bank_mask:0xf
	v_cndmask_b32_e64 v236, v235, v209, s[40:41]
	v_cndmask_b32_e64 v237, v213, v234, s[40:41]
	v_cvt_pk_bf16_f32 v241, v236, v237
	v_mov_b32_dpp v232, v210 quad_perm:[1,0,3,2] row_mask:0xf bank_mask:0xf
	v_mov_b32_dpp v233, v214 quad_perm:[1,0,3,2] row_mask:0xf bank_mask:0xf
	v_cndmask_b32_e64 v236, v233, v210, s[40:41]
	v_cndmask_b32_e64 v237, v214, v232, s[40:41]
	v_cvt_pk_bf16_f32 v242, v236, v237
	v_mov_b32_dpp v234, v211 quad_perm:[1,0,3,2] row_mask:0xf bank_mask:0xf
	v_mov_b32_dpp v235, v215 quad_perm:[1,0,3,2] row_mask:0xf bank_mask:0xf
	v_cndmask_b32_e64 v236, v235, v211, s[40:41]
	v_cndmask_b32_e64 v237, v215, v234, s[40:41]
	v_cvt_pk_bf16_f32 v243, v236, v237
	global_store_dword v6, v240, s[30:31] offset:-4096
	global_store_dword v6, v241, s[30:31] offset:0
	global_store_dword v7, v242, s[30:31] offset:-4096
	global_store_dword v7, v243, s[30:31] offset:0
	s_add_u32 s44, s30, 0x40000
	s_addc_u32 s45, s31, 0
	s_mov_b64 s[30:31], s[44:45]
	s_waitcnt vmcnt(30)
	s_waitcnt lgkmcnt(7)
	v_mfma_f32_16x16x32_bf16 v[208:211], v[16:19], v[160:163], 0
	s_waitcnt lgkmcnt(6)
	v_mfma_f32_16x16x32_bf16 v[212:215], v[16:19], v[176:179], 0
	s_waitcnt lgkmcnt(5)
	v_mfma_f32_16x16x32_bf16 v[208:211], v[20:23], v[164:167], v[208:211]
	s_waitcnt lgkmcnt(4)
	v_mfma_f32_16x16x32_bf16 v[212:215], v[20:23], v[180:183], v[212:215]
	s_waitcnt lgkmcnt(3)
	v_mfma_f32_16x16x32_bf16 v[208:211], v[24:27], v[168:171], v[208:211]
	s_waitcnt lgkmcnt(2)
	v_mfma_f32_16x16x32_bf16 v[212:215], v[24:27], v[184:187], v[212:215]
	s_waitcnt lgkmcnt(1)
	v_mfma_f32_16x16x32_bf16 v[208:211], v[28:31], v[172:175], v[208:211]
	s_waitcnt lgkmcnt(0)
	v_mfma_f32_16x16x32_bf16 v[212:215], v[28:31], v[188:191], v[212:215]
	s_barrier
	ds_read_b128 v[192:195], v10 offset:0
	ds_read_b128 v[200:203], v10 offset:2304
	ds_read_b128 v[196:199], v10 offset:64
	ds_read_b128 v[204:207], v10 offset:2368
	v_pk_mul_f32 v[216:217], v[216:217], v[48:49] op_sel_hi:[1,0]
	v_pk_mul_f32 v[218:219], v[218:219], v[48:49] op_sel_hi:[1,0]
	v_pk_mul_f32 v[220:221], v[220:221], v[48:49] op_sel_hi:[1,0]
	v_pk_mul_f32 v[222:223], v[222:223], v[48:49] op_sel_hi:[1,0]
	s_waitcnt lgkmcnt(3)
	v_mfma_f32_16x16x32_bf16 v[216:219], v[32:35], v[192:195], v[216:219]
	s_waitcnt lgkmcnt(2)
	v_mfma_f32_16x16x32_bf16 v[220:223], v[32:35], v[200:203], v[220:223]
	s_waitcnt lgkmcnt(1)
	v_mfma_f32_16x16x32_bf16 v[216:219], v[36:39], v[196:199], v[216:219]
	s_waitcnt lgkmcnt(0)
	v_mfma_f32_16x16x32_bf16 v[220:223], v[36:39], v[204:207], v[220:223]
	s_nop 7
	v_cvt_pk_bf16_f32 v228, v216, v217
	v_cvt_pk_bf16_f32 v229, v218, v219
	v_cvt_pk_bf16_f32 v230, v220, v221
	v_cvt_pk_bf16_f32 v231, v222, v223
	ds_write_b64 v11, v[228:229]
	ds_write_b64 v11, v[230:231] offset:4352
	global_load_dwordx4 v[118:121], v2, s[16:17] offset:0
	global_load_dwordx4 v[122:125], v2, s[16:17] offset:1024
	global_load_dwordx4 v[126:129], v2, s[16:17] offset:2048
	global_load_dwordx4 v[130:133], v2, s[16:17] offset:3072
	global_load_dwordx4 v[134:137], v3, s[18:19] offset:0
	global_load_dwordx4 v[138:141], v3, s[18:19] offset:1024
	global_load_dwordx4 v[142:145], v4, s[20:21]
	global_load_dwordx4 v[146:149], v4, s[20:21] offset:1024
	global_load_dword v150, v5, s[28:29]
	s_add_u32 s16, s16, 0x4000
	s_addc_u32 s17, s17, 0
	s_add_u32 s18, s18, 0x4000
	s_addc_u32 s19, s19, 0
	s_add_u32 s20, s20, s35
	s_addc_u32 s21, s21, 0
	s_add_u32 s28, s28, 4
	s_addc_u32 s29, s29, 0
	s_waitcnt lgkmcnt(0)
	s_barrier
	v_mfma_f32_16x16x32_bf16 v[208:211], v[40:43], v[192:195], v[208:211]
	v_mfma_f32_16x16x32_bf16 v[208:211], v[44:47], v[196:199], v[208:211]
	v_mfma_f32_16x16x32_bf16 v[212:215], v[40:43], v[200:203], v[212:215]
	v_mfma_f32_16x16x32_bf16 v[212:215], v[44:47], v[204:207], v[212:215]
	s_nop 7
	v_mov_b32_dpp v232, v208 quad_perm:[1,0,3,2] row_mask:0xf bank_mask:0xf
	v_mov_b32_dpp v233, v212 quad_perm:[1,0,3,2] row_mask:0xf bank_mask:0xf
	v_cndmask_b32_e64 v236, v233, v208, s[40:41]
	v_cndmask_b32_e64 v237, v212, v232, s[40:41]
	v_cvt_pk_bf16_f32 v240, v236, v237
	v_mov_b32_dpp v234, v209 quad_perm:[1,0,3,2] row_mask:0xf bank_mask:0xf
	v_mov_b32_dpp v235, v213 quad_perm:[1,0,3,2] row_mask:0xf bank_mask:0xf
	v_cndmask_b32_e64 v236, v235, v209, s[40:41]
	v_cndmask_b32_e64 v237, v213, v234, s[40:41]
	v_cvt_pk_bf16_f32 v241, v236, v237
	v_mov_b32_dpp v232, v210 quad_perm:[1,0,3,2] row_mask:0xf bank_mask:0xf
	v_mov_b32_dpp v233, v214 quad_perm:[1,0,3,2] row_mask:0xf bank_mask:0xf
	v_cndmask_b32_e64 v236, v233, v210, s[40:41]
	v_cndmask_b32_e64 v237, v214, v232, s[40:41]
	v_cvt_pk_bf16_f32 v242, v236, v237
	v_mov_b32_dpp v234, v211 quad_perm:[1,0,3,2] row_mask:0xf bank_mask:0xf
	v_mov_b32_dpp v235, v215 quad_perm:[1,0,3,2] row_mask:0xf bank_mask:0xf
	v_cndmask_b32_e64 v236, v235, v211, s[40:41]
	v_cndmask_b32_e64 v237, v215, v234, s[40:41]
	v_cvt_pk_bf16_f32 v243, v236, v237
	global_store_dword v6, v240, s[30:31] offset:-4096
	global_store_dword v6, v241, s[30:31] offset:0
	global_store_dword v7, v242, s[30:31] offset:-4096
	global_store_dword v7, v243, s[30:31] offset:0
; __device__ __forceinline__ unsigned xb_ld(unsigned* p)              { return __hip_atomic_load(p, __ATOMIC_RELAXED, __HIP_MEMORY_SCOPE_AGENT); }
; __device__ __forceinline__ unsigned xb_add(unsigned* p, unsigned v) { return __hip_atomic_fetch_add(p, v, __ATOMIC_RELAXED, __HIP_MEMORY_SCOPE_AGENT); }
; #define XB_SPIN(cond, bar) do { unsigned _sp = 0; while (cond) { __builtin_amdgcn_s_sleep(1); \
;     if ((++_sp & 255u) == 0u) { if (xb_ld(&(bar)[XB_TMO])) break; if (_sp > XB_SPIN_CAP) { atomicAdd(&(bar)[XB_TMO], 1u); break; } } } } while (0)
; __device__ __forceinline__ void xcd_barrier(const XcdBarrier& b) {
;     asm volatile("s_waitcnt vmcnt(0)" ::: "memory");
;     __syncthreads();
;     if (threadIdx.x == 0) {
;         unsigned* bar = b.bar;
;         __builtin_amdgcn_s_waitcnt(0);
;         unsigned nloc = b.st[0], nx = b.st[1];
;         if (nloc == 0u) { xcd_barrier_complete(bar, b.x, nloc, nx); b.st[0] = nloc; b.st[1] = nx; }
;         const unsigned old = xb_add(&bar[XB_XSUB(b.x)], 1u);
;         const unsigned gen = old / nloc;
;         if (old + 1u == (gen + 1u) * nloc) {
;             __builtin_amdgcn_fence(__ATOMIC_RELEASE, "agent");
;             asm volatile("s_waitcnt vmcnt(0)" ::: "memory");
;             const unsigned og = xb_add(&bar[XB_TOP], 1u);
;             const unsigned tg = og / nx;
;             if (og + 1u == (tg + 1u) * nx) xb_add(&bar[XB_TOPGEN], 1u);
;             else XB_SPIN(xb_ld(&bar[XB_TOPGEN]) == tg, bar);
;             __builtin_amdgcn_fence(__ATOMIC_ACQUIRE, "agent");
;             xb_add(&bar[XB_XGEN(b.x)], 1u);
;             asm volatile("s_waitcnt vmcnt(0)" ::: "memory");
;         } else {
;             XB_SPIN(xb_ld(&bar[XB_XGEN(b.x)]) == gen, bar);
;             __builtin_amdgcn_fence(__ATOMIC_ACQUIRE, "agent");
;             asm volatile("s_waitcnt vmcnt(0)" ::: "memory");
;         }
;     }
;     __syncthreads();
; }
.Lp3_done:
.LBB0_800:
	v_readlane_b32 s4, v255, 5
	v_readlane_b32 s5, v255, 6
	s_cmp_lt_i32 s5, 5
	s_cbranch_scc1 .LBB0_850
	s_waitcnt vmcnt(0)
	v_cmp_eq_u32_e32 vcc, 0, v0
	s_waitcnt vmcnt(0)
	s_barrier
	s_and_saveexec_b64 s[2:3], vcc
	s_cbranch_execz .LBB0_849
	v_readlane_b32 s0, v255, 8
	s_waitcnt vmcnt(0) expcnt(0) lgkmcnt(0)
	s_nop 0
	v_mov_b32_e32 v1, s0
	ds_read_b32 v3, v1
	ds_read_b32 v1, v1 offset:4
	s_waitcnt lgkmcnt(1)
	v_cmp_ne_u32_e32 vcc, 0, v3
	s_cbranch_vccnz .LBB0_817
	v_readlane_b32 s4, v255, 0
	v_readlane_b32 s5, v255, 1
	s_load_dwordx2 s[0:1], s[4:5], 0x4
	s_add_u32 s4, s26, 0x4200
	s_addc_u32 s5, s27, 0
	s_add_u32 s6, s26, 0x4400
	s_addc_u32 s7, s27, 0
	s_add_u32 s8, s26, 0x4500
	s_addc_u32 s9, s27, 0
	s_add_u32 s16, s26, 0x4600
	s_addc_u32 s17, s27, 0
	s_add_u32 s18, s26, 0x4700
	s_addc_u32 s19, s27, 0
	s_add_u32 s20, s26, 0x4800
	s_addc_u32 s21, s27, 0
	s_add_u32 s28, s26, 0x4900
	s_addc_u32 s29, s27, 0
	s_add_u32 s30, s26, 0x4a00
	s_addc_u32 s31, s27, 0
	s_add_u32 s38, s26, 0x4b00
	s_addc_u32 s39, s27, 0
	s_add_u32 s40, s26, 0x4c00
	s_addc_u32 s41, s27, 0
	s_add_u32 s42, s26, 0x4d00
	s_addc_u32 s43, s27, 0
	s_add_u32 s44, s26, 0x4e00
	s_addc_u32 s45, s27, 0
	s_add_u32 s46, s26, 0x4f00
	s_addc_u32 s47, s27, 0
	s_add_u32 s48, s26, 0x5000
	s_addc_u32 s49, s27, 0
	s_add_u32 s50, s26, 0x5100
	s_addc_u32 s51, s27, 0
	s_add_u32 s66, s26, 0x5200
	s_addc_u32 s67, s27, 0
	s_waitcnt lgkmcnt(0)
	s_mul_i32 s0, s0, s52
	s_add_u32 s68, s26, 0x5300
	s_mul_i32 s0, s0, s1
	s_addc_u32 s69, s27, 0
	s_mov_b32 s1, 1
	v_mov_b32_e32 v17, 0
	s_branch .LBB0_805
